# speedup vs baseline: 1.0081x; 1.0021x over previous
; __device__ __forceinline__ unsigned pk2(float lo, float hi) { f32x2_t v = {lo, hi}; bf16x2_t b = __builtin_convertvector(v, bf16x2_t); return __builtin_bit_cast(unsigned, b); }
; __device__ __forceinline__ float xsum32(float v) { auto rr = __builtin_amdgcn_permlane32_swap(__float_as_uint(v), __float_as_uint(v), false, false); return __uint_as_float(rr[0]) + __uint_as_float(rr[1]); }
; template <int DQK>
; __device__ __forceinline__ void attn_unit64(LAS char* lds, const bf16x8 (&qa)[DQK / 16], const bf16x8 (&qb)[DQK / 16],
;                                             const bf16_t* Kg, int ldk, const bf16_t* Vg, int ldv, int t0, int t1, bf16_t* Oga, int ogb_off) {
;     ...
;     float la = la0 + la1, lb = lb0 + lb1;
;     la = xsum32(la); lb = xsum32(lb);
;     const float ia = 1.0f / la, ib = 1.0f / lb;
; #pragma unroll
;     for (int g4 = 0; g4 < 4; ++g4) {
;         u32x2 w0, w1;
;         w0.x = pk2(oa0[4 * g4] * ia, oa0[4 * g4 + 1] * ia); w0.y = pk2(oa0[4 * g4 + 2] * ia, oa0[4 * g4 + 3] * ia);
;         w1.x = pk2(oa1[4 * g4] * ia, oa1[4 * g4 + 1] * ia); w1.y = pk2(oa1[4 * g4 + 2] * ia, oa1[4 * g4 + 3] * ia);
;         *(u32x2*)(Oga + 8 * g4 + 4 * h) = w0; *(u32x2*)(Oga + 32 + 8 * g4 + 4 * h) = w1;
;         w0.x = pk2(ob0[4 * g4] * ib, ob0[4 * g4 + 1] * ib); w0.y = pk2(ob0[4 * g4 + 2] * ib, ob0[4 * g4 + 3] * ib);
;         w1.x = pk2(ob1[4 * g4] * ib, ob1[4 * g4 + 1] * ib); w1.y = pk2(ob1[4 * g4 + 2] * ib, ob1[4 * g4 + 3] * ib);
;         *(u32x2*)(Oga + ogb_off + 8 * g4 + 4 * h) = w0; *(u32x2*)(Oga + ogb_off + 32 + 8 * g4 + 4 * h) = w1;
;     }
.LBB0_1115:
	v_pk_add_f32 v[64:65], v[170:171], v[170:171] op_sel:[1,0] op_sel_hi:[0,1]
	v_mov_b32_e32 v65, v64
	s_nop 1
	v_permlane32_swap_b32_e32 v64, v65
	v_pk_add_f32 v[66:67], v[172:173], v[172:173] op_sel:[1,0] op_sel_hi:[0,1]
	v_add_f32_e32 v64, v64, v65
	v_div_scale_f32 v67, s[0:1], v64, v64, 1.0
	v_rcp_f32_e32 v68, v67
	v_mov_b32_e32 v65, v66
	s_nop 1
	v_permlane32_swap_b32_e32 v66, v65
	v_add_f32_e32 v65, v66, v65
	v_fma_f32 v66, -v67, v68, 1.0
	v_fmac_f32_e32 v68, v66, v68
	v_div_scale_f32 v66, vcc, 1.0, v64, 1.0
	v_mul_f32_e32 v69, v66, v68
	v_fma_f32 v70, -v67, v69, v66
	v_fmac_f32_e32 v69, v70, v68
	v_fma_f32 v66, -v67, v69, v66
	v_div_scale_f32 v67, s[0:1], v65, v65, 1.0
	v_rcp_f32_e32 v70, v67
	v_div_fmas_f32 v66, v66, v68, v69
	v_div_fixup_f32 v64, v66, v64, 1.0
	v_lshlrev_b32_e32 v160, 2, v174
	v_fma_f32 v66, -v67, v70, 1.0
	v_fmac_f32_e32 v70, v66, v70
	v_div_scale_f32 v66, vcc, 1.0, v65, 1.0
	v_mul_f32_e32 v68, v66, v70
	v_fma_f32 v69, -v67, v68, v66
	v_fmac_f32_e32 v68, v69, v70
	v_fma_f32 v66, -v67, v68, v66
	v_div_fmas_f32 v66, v66, v70, v68
	v_div_fixup_f32 v66, v66, v65, 1.0
	v_lshl_add_u64 v[68:69], v[162:163], 0, v[160:161]
	v_lshl_add_u64 v[70:71], v[164:165], 0, v[160:161]
	v_lshl_add_u64 v[72:73], v[68:69], 0, s[14:15]
	v_pk_mul_f32 v[32:33], v[32:33], v[64:65] op_sel_hi:[1,0]
	v_pk_mul_f32 v[34:35], v[34:35], v[64:65] op_sel_hi:[1,0]
	v_pk_mul_f32 v[36:37], v[36:37], v[64:65] op_sel_hi:[1,0]
	v_pk_mul_f32 v[38:39], v[38:39], v[64:65] op_sel_hi:[1,0]
	v_cvt_pk_bf16_f32 v32, v32, v33
	v_cvt_pk_bf16_f32 v33, v34, v35
	v_cvt_pk_bf16_f32 v34, v36, v37
	v_cvt_pk_bf16_f32 v35, v38, v39
	s_nop 1
	v_permlane32_swap_b32_e32 v32, v34
	v_permlane32_swap_b32_e32 v33, v35
	global_store_dwordx4 v[68:69], v[32:35], off
	v_pk_mul_f32 v[40:41], v[40:41], v[64:65] op_sel_hi:[1,0]
	v_pk_mul_f32 v[42:43], v[42:43], v[64:65] op_sel_hi:[1,0]
	v_pk_mul_f32 v[44:45], v[44:45], v[64:65] op_sel_hi:[1,0]
	v_pk_mul_f32 v[46:47], v[46:47], v[64:65] op_sel_hi:[1,0]
	v_cvt_pk_bf16_f32 v40, v40, v41
	v_cvt_pk_bf16_f32 v41, v42, v43
	v_cvt_pk_bf16_f32 v42, v44, v45
	v_cvt_pk_bf16_f32 v43, v46, v47
	s_nop 1
	v_permlane32_swap_b32_e32 v40, v42
	v_permlane32_swap_b32_e32 v41, v43
	global_store_dwordx4 v[68:69], v[40:43], off offset:32
	v_pk_mul_f32 v[48:49], v[48:49], v[64:65] op_sel_hi:[1,0]
	v_pk_mul_f32 v[50:51], v[50:51], v[64:65] op_sel_hi:[1,0]
	v_pk_mul_f32 v[52:53], v[52:53], v[64:65] op_sel_hi:[1,0]
	v_pk_mul_f32 v[54:55], v[54:55], v[64:65] op_sel_hi:[1,0]
	v_cvt_pk_bf16_f32 v48, v48, v49
	v_cvt_pk_bf16_f32 v49, v50, v51
	v_cvt_pk_bf16_f32 v50, v52, v53
	v_cvt_pk_bf16_f32 v51, v54, v55
	s_nop 1
	v_permlane32_swap_b32_e32 v48, v50
	v_permlane32_swap_b32_e32 v49, v51
	global_store_dwordx4 v[68:69], v[48:51], off offset:64
	v_pk_mul_f32 v[56:57], v[56:57], v[64:65] op_sel_hi:[1,0]
	v_pk_mul_f32 v[58:59], v[58:59], v[64:65] op_sel_hi:[1,0]
	v_pk_mul_f32 v[60:61], v[60:61], v[64:65] op_sel_hi:[1,0]
	v_pk_mul_f32 v[62:63], v[62:63], v[64:65] op_sel_hi:[1,0]
	v_cvt_pk_bf16_f32 v56, v56, v57
	v_cvt_pk_bf16_f32 v57, v58, v59
	v_cvt_pk_bf16_f32 v58, v60, v61
	v_cvt_pk_bf16_f32 v59, v62, v63
	s_nop 1
	v_permlane32_swap_b32_e32 v56, v58
	v_permlane32_swap_b32_e32 v57, v59
	global_store_dwordx4 v[68:69], v[56:59], off offset:96
	v_pk_mul_f32 v[16:17], v[16:17], v[66:67] op_sel_hi:[1,0]
	v_pk_mul_f32 v[18:19], v[18:19], v[66:67] op_sel_hi:[1,0]
	v_pk_mul_f32 v[20:21], v[20:21], v[66:67] op_sel_hi:[1,0]
	v_pk_mul_f32 v[22:23], v[22:23], v[66:67] op_sel_hi:[1,0]
	v_cvt_pk_bf16_f32 v16, v16, v17
	v_cvt_pk_bf16_f32 v17, v18, v19
	v_cvt_pk_bf16_f32 v18, v20, v21
	v_cvt_pk_bf16_f32 v19, v22, v23
	s_nop 1
	v_permlane32_swap_b32_e32 v16, v18
	v_permlane32_swap_b32_e32 v17, v19
	global_store_dwordx4 v[70:71], v[16:19], off
	v_pk_mul_f32 v[24:25], v[24:25], v[66:67] op_sel_hi:[1,0]
	v_pk_mul_f32 v[26:27], v[26:27], v[66:67] op_sel_hi:[1,0]
	v_pk_mul_f32 v[28:29], v[28:29], v[66:67] op_sel_hi:[1,0]
	v_pk_mul_f32 v[30:31], v[30:31], v[66:67] op_sel_hi:[1,0]
	v_cvt_pk_bf16_f32 v24, v24, v25
	v_cvt_pk_bf16_f32 v25, v26, v27
	v_cvt_pk_bf16_f32 v26, v28, v29
	v_cvt_pk_bf16_f32 v27, v30, v31
	s_nop 1
	v_permlane32_swap_b32_e32 v24, v26
	v_permlane32_swap_b32_e32 v25, v27
	global_store_dwordx4 v[70:71], v[24:27], off offset:32
	v_pk_mul_f32 v[0:1], v[0:1], v[66:67] op_sel_hi:[1,0]
	v_pk_mul_f32 v[2:3], v[2:3], v[66:67] op_sel_hi:[1,0]
	v_pk_mul_f32 v[4:5], v[4:5], v[66:67] op_sel_hi:[1,0]
	v_pk_mul_f32 v[6:7], v[6:7], v[66:67] op_sel_hi:[1,0]
	v_cvt_pk_bf16_f32 v0, v0, v1
	v_cvt_pk_bf16_f32 v1, v2, v3
	v_cvt_pk_bf16_f32 v2, v4, v5
	v_cvt_pk_bf16_f32 v3, v6, v7
	s_nop 1
	v_permlane32_swap_b32_e32 v0, v2
	v_permlane32_swap_b32_e32 v1, v3
	global_store_dwordx4 v[72:73], v[0:3], off
	v_pk_mul_f32 v[8:9], v[8:9], v[66:67] op_sel_hi:[1,0]
	v_pk_mul_f32 v[10:11], v[10:11], v[66:67] op_sel_hi:[1,0]
	v_pk_mul_f32 v[12:13], v[12:13], v[66:67] op_sel_hi:[1,0]
	v_pk_mul_f32 v[14:15], v[14:15], v[66:67] op_sel_hi:[1,0]
	v_cvt_pk_bf16_f32 v8, v8, v9
	v_cvt_pk_bf16_f32 v9, v10, v11
	v_cvt_pk_bf16_f32 v10, v12, v13
	v_cvt_pk_bf16_f32 v11, v14, v15
	s_nop 1
	v_permlane32_swap_b32_e32 v8, v10
	v_permlane32_swap_b32_e32 v9, v11
	global_store_dwordx4 v[72:73], v[8:11], off offset:32
	s_add_i32 s38, s38, 1
	s_mul_i32 s0, s38, s88
	s_add_i32 s4, s0, s80
	s_cmp_lt_i32 s4, s37
	s_cbranch_scc0 .LBB0_1112
